# v3 plus: trailing half (waves 4-7) keeps prio 1 for the first 4 of the 8 row groups of the GEMM3 epilogue (balances the two halves' epilogue finish against the leading half's tile-boundary work)
# speedup vs baseline: 1.0020x; 1.0020x over previous
; #define LAS __attribute__((address_space(3)))
; DEV u32x4 pack8(const float (&v)[8]) { u32x4 w; w.x = cvt_pk_bf16(v[0], v[1]); w.y = cvt_pk_bf16(v[2], v[3]); w.z = cvt_pk_bf16(v[4], v[5]); w.w = cvt_pk_bf16(v[6], v[7]); return w; }
; DEV void TileMap::operator()(int t, int& brow, int& bcol) const { int pm, pn; tile_map(t, nM, nN, pm, pn); brow = pm * 256; bcol = pn * 256; }
; DEV void TileG1::operator()(int t, int& brow, int& bcol) const { int pm, pn; tile_map(t, 192, 7, pm, pn); brow = pm * 256; bcol = (pn == 0 ? 6 : pn - 1) * 256; }
; DEV void TileMapRev::operator()(int t, int& brow, int& bcol) const { int pm, pn; tile_map(t, nM, nN, pm, pn); brow = (nM - 1 - pm) * 256; bcol = pn * 256; }
;     DEV void operator()(f32x4 (&acc)[2][2][4][2], int brow, int bcol, LAS unsigned char* lds, int par) const {
;         EPI_IDS
; #pragma unroll
;         for (int ai = 0; ai < 2; ++ai)
; #pragma unroll
;             for (int m = 0; m < 4; ++m) {
;                 const int lr = ai * 128 + wr * 64 + m * 16 + fr, row = brow + lr;
;                 const f32x4 s4 = *(const LAS f32x4*)(lds + LDS_EX + par * 4096 + lr * 16);
;                 const float rs = rsqrtf(((s4[0] + s4[1]) + (s4[2] + s4[3])) * (1.0f / 1024.0f) + EPS);
;                 float o[8];
;                 const float rs2 = rs * rs, ce = rs * -1.4426950408889634f;
; #pragma unroll
;                 for (int bj = 0; bj < 2; ++bj) {
;                     const f32x4 g = acc[ai][bj][m][0], u = acc[ai][bj][m][1];
; #pragma unroll
;                     for (int j = 0; j < 4; ++j) o[bj * 4 + j] = (g[j] * u[j]) * rs2 * __builtin_amdgcn_rcpf(1.0f + __builtin_amdgcn_exp2f(g[j] * ce));
;                 }
;                 *(u32x4*)(act + (size_t)row * DFF + (bcol >> 1) + wc * 32 + fq * 8) = pack8(o);
;             }
.LBB0_1341:
	s_or_b64 exec, exec, s[8:9]
	s_cmp_lt_u32 s100, 0x100
	s_cbranch_scc1 .Lep3_skip
	s_setprio 1
.Lep3_skip:
	v_mov_b32_e32 v137, v188
	s_movk_i32 s8, 0xffc0
	v_and_b32_e32 v136, 15, v137
	v_ashrrev_i32_e32 v138, 2, v137
	v_and_or_b32 v136, v138, s8, v136
	s_lshl_b32 s8, s4, 12
	s_add_i32 s8, s8, 0
	s_add_i32 s8, s8, 0x20000
	v_lshl_add_u32 v138, v136, 4, s8
	ds_read_b128 v[158:161], v138
	v_mul_f32_e32 v120, v124, v120
	v_mul_f32_e32 v121, v125, v121
	v_mul_f32_e32 v122, v126, v122
	v_mul_f32_e32 v123, v127, v123
	s_waitcnt lgkmcnt(0)
	v_mov_b32_e32 v138, v159
	v_mov_b32_e32 v139, v160
	v_mov_b32_e32 v159, v161
	v_pk_add_f32 v[138:139], v[138:139], v[158:159]
	v_mul_f32_e32 v159, v116, v112
	v_add_f32_e32 v138, v138, v139
	v_fmamk_f32 v138, v138, 0x3a800000, v189
	v_cmp_gt_f32_e32 vcc, s24, v138
	v_mul_f32_e32 v139, 0x4b800000, v138
	v_mul_f32_e32 v160, v117, v113
	v_cndmask_b32_e32 v138, v138, v139, vcc
	v_rsq_f32_e32 v138, v138
	s_ashr_i32 s30, s29, 1
	s_ashr_i32 s31, s30, 31
	s_lshl_b64 s[54:55], s[30:31], 1
	v_mul_f32_e32 v139, 0x45800000, v138
	v_cndmask_b32_e32 v139, v138, v139, vcc
	v_mul_f32_e32 v158, 0xbfb8aa3b, v139
	v_mul_f32_e32 v112, v116, v158
	v_exp_f32_e32 v112, v112
	v_mov_b32_e32 v138, v118
	v_mul_f32_e32 v118, v118, v158
	v_exp_f32_e32 v118, v118
	v_add_f32_e32 v112, 1.0, v112
	v_rcp_f32_e32 v116, v112
	v_mul_f32_e32 v112, v117, v158
	v_exp_f32_e32 v112, v112
	v_add_f32_e32 v118, 1.0, v118
	v_rcp_f32_e32 v118, v118
	v_mov_b32_e32 v113, v139
	v_add_f32_e32 v112, 1.0, v112
	v_rcp_f32_e32 v117, v112
	v_mov_b32_e32 v112, v114
	v_pk_mul_f32 v[112:113], v[138:139], v[112:113]
	v_mul_f32_e32 v124, v124, v158
	v_mul_f32_e32 v112, v112, v113
	v_mul_f32_e32 v114, v120, v113
	v_mul_f32_e32 v120, v121, v113
	v_mul_f32_e32 v121, v122, v113
	v_mul_f32_e32 v122, v123, v113
	v_mul_f32_e32 v123, v159, v113
	v_mul_f32_e32 v118, v112, v118
	v_mul_f32_e32 v112, v119, v115
	v_exp_f32_e32 v124, v124
	v_mul_f32_e32 v125, v125, v158
	v_mul_f32_e32 v116, v123, v116
	v_mul_f32_e32 v123, v160, v113
	v_mul_f32_e32 v112, v112, v113
	v_mul_f32_e32 v113, v119, v158
	v_exp_f32_e32 v125, v125
	v_exp_f32_e32 v113, v113
	v_mul_f32_e32 v126, v126, v158
	v_exp_f32_e32 v126, v126
	v_mul_f32_e32 v127, v127, v158
	v_add_f32_e32 v124, 1.0, v124
	v_exp_f32_e32 v127, v127
	v_rcp_f32_e32 v124, v124
	v_add_f32_e32 v125, 1.0, v125
	v_add_f32_e32 v113, 1.0, v113
	v_rcp_f32_e32 v125, v125
	v_rcp_f32_e32 v113, v113
	v_add_f32_e32 v126, 1.0, v126
	v_rcp_f32_e32 v126, v126
	v_add_f32_e32 v127, 1.0, v127
	v_rcp_f32_e32 v127, v127
	v_mul_f32_e32 v114, v114, v124
	v_mul_f32_e32 v117, v123, v117
	v_mul_f32_e32 v120, v120, v125
	v_mul_f32_e32 v115, v112, v113
	v_add_u32_e32 v119, s28, v136
	v_cvt_pk_bf16_f32 v112, v114, v120
	v_cvt_pk_bf16_f32 v114, v116, v117
	v_mov_b64_e32 v[116:117], s[70:71]
	v_cvt_pk_bf16_f32 v115, v118, v115
	v_mad_i64_i32 v[118:119], s[36:37], v119, s33, v[116:117]
	v_mul_f32_e32 v121, v121, v126
	v_lshl_add_u64 v[118:119], v[118:119], 0, s[54:55]
	v_and_b32_e32 v194, 0xc0, v137
	v_mul_f32_e32 v122, v122, v127
	v_cvt_pk_bf16_f32 v113, v121, v122
	v_lshl_add_u64 v[120:121], v[118:119], 0, v[194:195]
	v_and_b32_e32 v118, 48, v137
	v_mov_b32_e32 v119, v195
	v_lshl_add_u64 v[120:121], v[120:121], 0, v[118:119]
	global_store_dwordx4 v[120:121], v[112:115], off
	v_or_b32_e32 v120, 16, v136
	v_mul_f32_e32 v100, v96, v100
	v_lshl_add_u32 v112, v120, 4, s8
	ds_read_b128 v[112:115], v112
	v_mul_f32_e32 v108, v104, v108
	v_mul_f32_e32 v109, v105, v109
	v_mul_f32_e32 v110, v106, v110
	v_mul_f32_e32 v111, v107, v111
	s_waitcnt lgkmcnt(0)
	v_mov_b32_e32 v122, v113
	v_mov_b32_e32 v123, v114
	v_mov_b32_e32 v113, v115
	v_pk_add_f32 v[112:113], v[122:123], v[112:113]
	v_mul_f32_e32 v101, v97, v101
	v_add_f32_e32 v112, v112, v113
	v_fmamk_f32 v112, v112, 0x3a800000, v189
	v_cmp_gt_f32_e32 vcc, s24, v112
	v_mul_f32_e32 v113, 0x4b800000, v112
	v_mul_f32_e32 v88, v92, v88
	v_cndmask_b32_e32 v112, v112, v113, vcc
	v_rsq_f32_e32 v112, v112
	v_mul_f32_e32 v89, v93, v89
	v_mul_f32_e32 v90, v94, v90
	v_mul_f32_e32 v91, v95, v91
	v_mul_f32_e32 v113, 0x45800000, v112
	v_cndmask_b32_e32 v113, v112, v113, vcc
	v_mul_f32_e32 v114, 0xbfb8aa3b, v113
	v_mul_f32_e32 v96, v96, v114
	v_exp_f32_e32 v96, v96
	v_mul_f32_e32 v104, v104, v114
	v_exp_f32_e32 v104, v104
	v_mul_f32_e32 v105, v105, v114
	v_add_f32_e32 v96, 1.0, v96
	v_rcp_f32_e32 v115, v96
	v_mul_f32_e32 v96, v97, v114
	v_exp_f32_e32 v105, v105
	v_mul_f32_e32 v106, v106, v114
	v_exp_f32_e32 v96, v96
	v_exp_f32_e32 v106, v106
	v_mul_f32_e32 v107, v107, v114
	v_mov_b32_e32 v112, v98
	v_mul_f32_e32 v98, v98, v114
	v_exp_f32_e32 v107, v107
	v_exp_f32_e32 v98, v98
	v_add_f32_e32 v104, 1.0, v104
	v_rcp_f32_e32 v104, v104
	v_add_f32_e32 v105, 1.0, v105
	v_add_f32_e32 v96, 1.0, v96
	v_rcp_f32_e32 v105, v105
	v_add_f32_e32 v106, 1.0, v106
	v_rcp_f32_e32 v121, v96
	v_mov_b32_e32 v96, v102
	v_mov_b32_e32 v97, v113
	v_rcp_f32_e32 v106, v106
	v_add_f32_e32 v107, 1.0, v107
	v_pk_mul_f32 v[96:97], v[112:113], v[96:97]
	v_add_f32_e32 v98, 1.0, v98
	v_rcp_f32_e32 v107, v107
	v_mul_f32_e32 v102, v108, v97
	v_rcp_f32_e32 v98, v98
	v_mul_f32_e32 v102, v102, v104
	v_mul_f32_e32 v104, v109, v97
	v_mul_f32_e32 v104, v104, v105
	v_mul_f32_e32 v105, v110, v97
	v_mul_f32_e32 v105, v105, v106
	v_mul_f32_e32 v106, v111, v97
	v_mul_f32_e32 v96, v96, v97
	v_mul_f32_e32 v106, v106, v107
	v_mul_f32_e32 v107, v96, v98
	v_mul_f32_e32 v96, v99, v103
	v_mul_f32_e32 v100, v100, v97
	v_mul_f32_e32 v101, v101, v97
	v_mul_f32_e32 v96, v96, v97
	v_mul_f32_e32 v97, v99, v114
	v_exp_f32_e32 v97, v97
	v_mul_f32_e32 v100, v100, v115
	v_mul_f32_e32 v101, v101, v121
	v_add_u32_e32 v103, s28, v120
	v_add_f32_e32 v97, 1.0, v97
	v_rcp_f32_e32 v97, v97
	v_cvt_pk_bf16_f32 v98, v100, v101
	v_mad_i64_i32 v[100:101], s[30:31], v103, s33, v[116:117]
	v_lshl_add_u64 v[100:101], v[100:101], 0, s[54:55]
	v_lshl_add_u64 v[100:101], v[100:101], 0, v[194:195]
	v_mul_f32_e32 v99, v96, v97
	v_cvt_pk_bf16_f32 v96, v102, v104
	v_lshl_add_u64 v[100:101], v[100:101], 0, v[118:119]
	v_or_b32_e32 v102, 32, v136
	v_cvt_pk_bf16_f32 v97, v105, v106
	v_cvt_pk_bf16_f32 v99, v107, v99
	global_store_dwordx4 v[100:101], v[96:99], off
	v_mul_f32_e32 v68, v64, v68
	v_mul_f32_e32 v76, v72, v76
	v_lshl_add_u32 v96, v102, 4, s8
	ds_read_b128 v[96:99], v96
	v_mul_f32_e32 v77, v73, v77
	v_mul_f32_e32 v78, v74, v78
	v_mul_f32_e32 v79, v75, v79
	v_mul_f32_e32 v69, v65, v69
	s_waitcnt lgkmcnt(0)
; #define LAS __attribute__((address_space(3)))
; DEV u32x4 pack8(const float (&v)[8]) { u32x4 w; w.x = cvt_pk_bf16(v[0], v[1]); w.y = cvt_pk_bf16(v[2], v[3]); w.z = cvt_pk_bf16(v[4], v[5]); w.w = cvt_pk_bf16(v[6], v[7]); return w; }
; DEV void TileMap::operator()(int t, int& brow, int& bcol) const { int pm, pn; tile_map(t, nM, nN, pm, pn); brow = pm * 256; bcol = pn * 256; }
; DEV void TileG1::operator()(int t, int& brow, int& bcol) const { int pm, pn; tile_map(t, 192, 7, pm, pn); brow = pm * 256; bcol = (pn == 0 ? 6 : pn - 1) * 256; }
; DEV void TileMapRev::operator()(int t, int& brow, int& bcol) const { int pm, pn; tile_map(t, nM, nN, pm, pn); brow = (nM - 1 - pm) * 256; bcol = pn * 256; }
;     DEV void operator()(f32x4 (&acc)[2][2][4][2], int brow, int bcol, LAS unsigned char* lds, int par) const {
;         EPI_IDS
; #pragma unroll
;         for (int ai = 0; ai < 2; ++ai)
; #pragma unroll
;             for (int m = 0; m < 4; ++m) {
;                 const int lr = ai * 128 + wr * 64 + m * 16 + fr, row = brow + lr;
;                 const f32x4 s4 = *(const LAS f32x4*)(lds + LDS_EX + par * 4096 + lr * 16);
;                 const float rs = rsqrtf(((s4[0] + s4[1]) + (s4[2] + s4[3])) * (1.0f / 1024.0f) + EPS);
;                 float o[8];
;                 const float rs2 = rs * rs, ce = rs * -1.4426950408889634f;
; #pragma unroll
;                 for (int bj = 0; bj < 2; ++bj) {
;                     const f32x4 g = acc[ai][bj][m][0], u = acc[ai][bj][m][1];
; #pragma unroll
;                     for (int j = 0; j < 4; ++j) o[bj * 4 + j] = (g[j] * u[j]) * rs2 * __builtin_amdgcn_rcpf(1.0f + __builtin_amdgcn_exp2f(g[j] * ce));
;                 }
;                 *(u32x4*)(act + (size_t)row * DFF + (bcol >> 1) + wc * 32 + fq * 8) = pack8(o);
;             }
	v_mov_b32_e32 v100, v97
	v_mov_b32_e32 v101, v98
	v_mov_b32_e32 v97, v99
	v_pk_add_f32 v[96:97], v[100:101], v[96:97]
	v_mul_f32_e32 v99, v84, v80
	v_add_f32_e32 v96, v96, v97
	v_fmamk_f32 v96, v96, 0x3a800000, v189
	v_cmp_gt_f32_e32 vcc, s24, v96
	v_mul_f32_e32 v97, 0x4b800000, v96
	v_mul_f32_e32 v100, v85, v81
	v_cndmask_b32_e32 v96, v96, v97, vcc
	v_rsq_f32_e32 v96, v96
	v_mul_f32_e32 v56, v60, v56
	v_mul_f32_e32 v57, v61, v57
	v_mul_f32_e32 v58, v62, v58
	v_mul_f32_e32 v97, 0x45800000, v96
	v_cndmask_b32_e32 v97, v96, v97, vcc
	v_mul_f32_e32 v98, 0xbfb8aa3b, v97
	v_mul_f32_e32 v80, v84, v98
	v_exp_f32_e32 v80, v80
	v_mov_b32_e32 v96, v86
	v_mul_f32_e32 v86, v86, v98
	v_exp_f32_e32 v86, v86
	v_add_f32_e32 v80, 1.0, v80
	v_rcp_f32_e32 v84, v80
	v_mul_f32_e32 v80, v85, v98
	v_exp_f32_e32 v80, v80
	v_add_f32_e32 v86, 1.0, v86
	v_rcp_f32_e32 v86, v86
	v_mov_b32_e32 v81, v97
	v_add_f32_e32 v80, 1.0, v80
	v_rcp_f32_e32 v85, v80
	v_mov_b32_e32 v80, v82
	v_pk_mul_f32 v[80:81], v[96:97], v[80:81]
	v_mul_f32_e32 v92, v92, v98
	v_mul_f32_e32 v80, v80, v81
	v_mul_f32_e32 v82, v88, v81
	v_mul_f32_e32 v88, v89, v81
	v_mul_f32_e32 v89, v90, v81
	v_mul_f32_e32 v90, v91, v81
	v_mul_f32_e32 v91, v99, v81
	v_mul_f32_e32 v86, v80, v86
	v_mul_f32_e32 v80, v87, v83
	v_exp_f32_e32 v92, v92
	v_mul_f32_e32 v93, v93, v98
	v_mul_f32_e32 v84, v91, v84
	v_mul_f32_e32 v91, v100, v81
	v_mul_f32_e32 v80, v80, v81
	v_mul_f32_e32 v81, v87, v98
	v_exp_f32_e32 v93, v93
	v_exp_f32_e32 v81, v81
	v_add_f32_e32 v92, 1.0, v92
	v_mul_f32_e32 v94, v94, v98
	v_mul_f32_e32 v95, v95, v98
	v_rcp_f32_e32 v92, v92
	v_add_f32_e32 v93, 1.0, v93
	v_exp_f32_e32 v94, v94
	v_exp_f32_e32 v95, v95
	v_add_f32_e32 v81, 1.0, v81
	v_rcp_f32_e32 v93, v93
	v_rcp_f32_e32 v81, v81
	v_add_f32_e32 v94, 1.0, v94
	v_add_f32_e32 v95, 1.0, v95
	v_mul_f32_e32 v82, v82, v92
	v_mul_f32_e32 v85, v91, v85
	v_add_u32_e32 v87, s28, v102
	v_rcp_f32_e32 v94, v94
	v_rcp_f32_e32 v95, v95
	v_mul_f32_e32 v88, v88, v93
	v_mul_f32_e32 v83, v80, v81
	v_cvt_pk_bf16_f32 v80, v82, v88
	v_cvt_pk_bf16_f32 v82, v84, v85
	v_mad_i64_i32 v[84:85], s[30:31], v87, s33, v[116:117]
	v_lshl_add_u64 v[84:85], v[84:85], 0, s[54:55]
	v_lshl_add_u64 v[84:85], v[84:85], 0, v[194:195]
	v_cvt_pk_bf16_f32 v83, v86, v83
	v_lshl_add_u64 v[84:85], v[84:85], 0, v[118:119]
	v_or_b32_e32 v86, 48, v136
	v_mul_f32_e32 v89, v89, v94
	v_mul_f32_e32 v90, v90, v95
	v_cvt_pk_bf16_f32 v81, v89, v90
	global_store_dwordx4 v[84:85], v[80:83], off
	v_mul_f32_e32 v59, v63, v59
	v_mul_f32_e32 v36, v32, v36
	v_lshl_add_u32 v80, v86, 4, s8
	ds_read_b128 v[80:83], v80
	v_mul_f32_e32 v44, v40, v44
	v_mul_f32_e32 v45, v41, v45
	v_mul_f32_e32 v46, v42, v46
	v_mul_f32_e32 v47, v43, v47
	s_waitcnt lgkmcnt(0)
	v_mov_b32_e32 v84, v81
	v_mov_b32_e32 v85, v82
	v_mov_b32_e32 v81, v83
	v_pk_add_f32 v[80:81], v[84:85], v[80:81]
	v_mul_f32_e32 v37, v33, v37
	v_add_f32_e32 v80, v80, v81
	v_fmamk_f32 v80, v80, 0x3a800000, v189
	v_cmp_gt_f32_e32 vcc, s24, v80
	v_mul_f32_e32 v81, 0x4b800000, v80
	v_mul_f32_e32 v24, v28, v24
	v_cndmask_b32_e32 v80, v80, v81, vcc
	v_rsq_f32_e32 v80, v80
	v_mul_f32_e32 v25, v29, v25
	v_mul_f32_e32 v26, v30, v26
	v_mul_f32_e32 v27, v31, v27
	v_mul_f32_e32 v81, 0x45800000, v80
	v_cndmask_b32_e32 v81, v80, v81, vcc
	v_mul_f32_e32 v82, 0xbfb8aa3b, v81
	v_mul_f32_e32 v64, v64, v82
	v_exp_f32_e32 v64, v64
	v_mul_f32_e32 v72, v72, v82
	v_exp_f32_e32 v72, v72
	v_mul_f32_e32 v73, v73, v82
	v_add_f32_e32 v64, 1.0, v64
	v_rcp_f32_e32 v83, v64
	v_mul_f32_e32 v64, v65, v82
	v_exp_f32_e32 v73, v73
	v_mul_f32_e32 v74, v74, v82
	v_exp_f32_e32 v64, v64
	v_exp_f32_e32 v74, v74
	v_mul_f32_e32 v75, v75, v82
	v_mov_b32_e32 v80, v66
	v_mul_f32_e32 v66, v66, v82
	v_exp_f32_e32 v75, v75
	v_exp_f32_e32 v66, v66
	v_add_f32_e32 v72, 1.0, v72
	v_rcp_f32_e32 v72, v72
	v_add_f32_e32 v73, 1.0, v73
	v_add_f32_e32 v64, 1.0, v64
	v_rcp_f32_e32 v73, v73
	v_add_f32_e32 v74, 1.0, v74
	v_rcp_f32_e32 v84, v64
	v_mov_b32_e32 v64, v70
	v_mov_b32_e32 v65, v81
	v_rcp_f32_e32 v74, v74
	v_add_f32_e32 v75, 1.0, v75
	v_pk_mul_f32 v[64:65], v[80:81], v[64:65]
	v_add_f32_e32 v66, 1.0, v66
	v_rcp_f32_e32 v75, v75
	v_mul_f32_e32 v70, v76, v65
	v_rcp_f32_e32 v66, v66
	v_mul_f32_e32 v70, v70, v72
	v_mul_f32_e32 v72, v77, v65
	v_mul_f32_e32 v72, v72, v73
	v_mul_f32_e32 v73, v78, v65
	v_mul_f32_e32 v73, v73, v74
	v_mul_f32_e32 v74, v79, v65
	v_mul_f32_e32 v64, v64, v65
	v_mul_f32_e32 v74, v74, v75
	v_mul_f32_e32 v75, v64, v66
	v_mul_f32_e32 v64, v67, v71
	v_mul_f32_e32 v68, v68, v65
	v_mul_f32_e32 v69, v69, v65
	v_mul_f32_e32 v64, v64, v65
	v_mul_f32_e32 v65, v67, v82
	v_exp_f32_e32 v65, v65
	v_mul_f32_e32 v68, v68, v83
	v_mul_f32_e32 v69, v69, v84
	v_add_u32_e32 v71, s28, v86
	v_add_f32_e32 v65, 1.0, v65
	v_rcp_f32_e32 v65, v65
	v_cvt_pk_bf16_f32 v66, v68, v69
	v_mad_i64_i32 v[68:69], s[30:31], v71, s33, v[116:117]
	v_lshl_add_u64 v[68:69], v[68:69], 0, s[54:55]
	v_lshl_add_u64 v[68:69], v[68:69], 0, v[194:195]
	v_mul_f32_e32 v67, v64, v65
	v_cvt_pk_bf16_f32 v64, v70, v72
	v_lshl_add_u64 v[68:69], v[68:69], 0, v[118:119]
	v_add_u32_e32 v70, 0x80, v136
	v_cvt_pk_bf16_f32 v65, v73, v74
	v_cvt_pk_bf16_f32 v67, v75, v67
	global_store_dwordx4 v[68:69], v[64:67], off
	s_setprio 0
	v_mul_f32_e32 v4, v0, v4
	v_mul_f32_e32 v12, v8, v12
	v_lshl_add_u32 v64, v70, 4, s8
	ds_read_b128 v[64:67], v64
	v_mul_f32_e32 v13, v9, v13
	v_mul_f32_e32 v14, v10, v14
	v_mul_f32_e32 v15, v11, v15
	v_mul_f32_e32 v5, v1, v5
	s_waitcnt lgkmcnt(0)
; #define LAS __attribute__((address_space(3)))
; DEV u32x4 pack8(const float (&v)[8]) { u32x4 w; w.x = cvt_pk_bf16(v[0], v[1]); w.y = cvt_pk_bf16(v[2], v[3]); w.z = cvt_pk_bf16(v[4], v[5]); w.w = cvt_pk_bf16(v[6], v[7]); return w; }
; DEV void TileMap::operator()(int t, int& brow, int& bcol) const { int pm, pn; tile_map(t, nM, nN, pm, pn); brow = pm * 256; bcol = pn * 256; }
; DEV void TileG1::operator()(int t, int& brow, int& bcol) const { int pm, pn; tile_map(t, 192, 7, pm, pn); brow = pm * 256; bcol = (pn == 0 ? 6 : pn - 1) * 256; }
; DEV void TileMapRev::operator()(int t, int& brow, int& bcol) const { int pm, pn; tile_map(t, nM, nN, pm, pn); brow = (nM - 1 - pm) * 256; bcol = pn * 256; }
;     DEV void operator()(f32x4 (&acc)[2][2][4][2], int brow, int bcol, LAS unsigned char* lds, int par) const {
;         EPI_IDS
; #pragma unroll
;         for (int ai = 0; ai < 2; ++ai)
; #pragma unroll
;             for (int m = 0; m < 4; ++m) {
;                 const int lr = ai * 128 + wr * 64 + m * 16 + fr, row = brow + lr;
;                 const f32x4 s4 = *(const LAS f32x4*)(lds + LDS_EX + par * 4096 + lr * 16);
;                 const float rs = rsqrtf(((s4[0] + s4[1]) + (s4[2] + s4[3])) * (1.0f / 1024.0f) + EPS);
;                 float o[8];
;                 const float rs2 = rs * rs, ce = rs * -1.4426950408889634f;
; #pragma unroll
;                 for (int bj = 0; bj < 2; ++bj) {
;                     const f32x4 g = acc[ai][bj][m][0], u = acc[ai][bj][m][1];
; #pragma unroll
;                     for (int j = 0; j < 4; ++j) o[bj * 4 + j] = (g[j] * u[j]) * rs2 * __builtin_amdgcn_rcpf(1.0f + __builtin_amdgcn_exp2f(g[j] * ce));
;                 }
;                 *(u32x4*)(act + (size_t)row * DFF + (bcol >> 1) + wc * 32 + fq * 8) = pack8(o);
;             }
	v_mov_b32_e32 v68, v65
	v_mov_b32_e32 v69, v66
	v_mov_b32_e32 v65, v67
	v_pk_add_f32 v[64:65], v[68:69], v[64:65]
	v_mul_f32_e32 v67, v52, v48
	v_add_f32_e32 v64, v64, v65
	v_fmamk_f32 v64, v64, 0x3a800000, v189
	v_cmp_gt_f32_e32 vcc, s24, v64
	v_mul_f32_e32 v65, 0x4b800000, v64
	v_mul_f32_e32 v68, v53, v49
	v_cndmask_b32_e32 v64, v64, v65, vcc
	v_rsq_f32_e32 v64, v64
	v_readlane_b32 s97, v250, 13
	v_mul_f32_e32 v65, 0x45800000, v64
	v_cndmask_b32_e32 v65, v64, v65, vcc
	v_mul_f32_e32 v66, 0xbfb8aa3b, v65
	v_mul_f32_e32 v48, v52, v66
	v_exp_f32_e32 v48, v48
	v_mov_b32_e32 v64, v54
	v_mul_f32_e32 v54, v54, v66
	v_exp_f32_e32 v54, v54
	v_add_f32_e32 v48, 1.0, v48
	v_rcp_f32_e32 v52, v48
	v_mul_f32_e32 v48, v53, v66
	v_exp_f32_e32 v48, v48
	v_add_f32_e32 v54, 1.0, v54
	v_rcp_f32_e32 v54, v54
	v_mov_b32_e32 v49, v65
	v_add_f32_e32 v48, 1.0, v48
	v_rcp_f32_e32 v53, v48
	v_mov_b32_e32 v48, v50
	v_pk_mul_f32 v[48:49], v[64:65], v[48:49]
	v_mul_f32_e32 v60, v60, v66
	v_mul_f32_e32 v48, v48, v49
	v_mul_f32_e32 v50, v56, v49
	v_mul_f32_e32 v56, v57, v49
	v_mul_f32_e32 v57, v58, v49
	v_mul_f32_e32 v58, v59, v49
	v_mul_f32_e32 v59, v67, v49
	v_mul_f32_e32 v54, v48, v54
	v_mul_f32_e32 v48, v55, v51
	v_exp_f32_e32 v60, v60
	v_mul_f32_e32 v61, v61, v66
	v_mul_f32_e32 v52, v59, v52
	v_mul_f32_e32 v59, v68, v49
	v_mul_f32_e32 v48, v48, v49
	v_mul_f32_e32 v49, v55, v66
	v_exp_f32_e32 v61, v61
	v_exp_f32_e32 v49, v49
	v_add_f32_e32 v60, 1.0, v60
	v_mul_f32_e32 v62, v62, v66
	v_mul_f32_e32 v63, v63, v66
	v_rcp_f32_e32 v60, v60
	v_add_f32_e32 v61, 1.0, v61
	v_exp_f32_e32 v62, v62
	v_exp_f32_e32 v63, v63
	v_add_f32_e32 v49, 1.0, v49
	v_rcp_f32_e32 v61, v61
	v_rcp_f32_e32 v49, v49
	v_add_f32_e32 v62, 1.0, v62
	v_add_f32_e32 v63, 1.0, v63
	v_mul_f32_e32 v50, v50, v60
	v_mul_f32_e32 v53, v59, v53
	v_add_u32_e32 v55, s28, v70
	v_rcp_f32_e32 v62, v62
	v_rcp_f32_e32 v63, v63
	v_mul_f32_e32 v56, v56, v61
	v_mul_f32_e32 v51, v48, v49
	v_cvt_pk_bf16_f32 v48, v50, v56
	v_cvt_pk_bf16_f32 v50, v52, v53
	v_mad_i64_i32 v[52:53], s[30:31], v55, s33, v[116:117]
	v_lshl_add_u64 v[52:53], v[52:53], 0, s[54:55]
	v_lshl_add_u64 v[52:53], v[52:53], 0, v[194:195]
	v_cvt_pk_bf16_f32 v51, v54, v51
	v_lshl_add_u64 v[52:53], v[52:53], 0, v[118:119]
	v_add_u32_e32 v54, 0x90, v136
	v_mul_f32_e32 v57, v57, v62
	v_mul_f32_e32 v58, v58, v63
	v_cvt_pk_bf16_f32 v49, v57, v58
	global_store_dwordx4 v[52:53], v[48:51], off
	s_nop 1
	v_lshl_add_u32 v48, v54, 4, s8
	ds_read_b128 v[48:51], v48
	s_waitcnt lgkmcnt(0)
	v_mov_b32_e32 v52, v49
	v_mov_b32_e32 v53, v50
	v_mov_b32_e32 v49, v51
	v_pk_add_f32 v[48:49], v[52:53], v[48:49]
	s_nop 0
	v_add_f32_e32 v48, v48, v49
	v_fmamk_f32 v48, v48, 0x3a800000, v189
	v_cmp_gt_f32_e32 vcc, s24, v48
	v_mul_f32_e32 v49, 0x4b800000, v48
	s_nop 0
	v_cndmask_b32_e32 v48, v48, v49, vcc
	v_rsq_f32_e32 v48, v48
	s_nop 0
	v_mul_f32_e32 v49, 0x45800000, v48
	v_cndmask_b32_e32 v49, v48, v49, vcc
	v_mul_f32_e32 v50, 0xbfb8aa3b, v49
	v_mul_f32_e32 v32, v32, v50
	v_exp_f32_e32 v32, v32
	v_mul_f32_e32 v40, v40, v50
	v_exp_f32_e32 v40, v40
	v_mul_f32_e32 v41, v41, v50
	v_add_f32_e32 v32, 1.0, v32
	v_rcp_f32_e32 v51, v32
	v_mul_f32_e32 v32, v33, v50
	v_exp_f32_e32 v41, v41
	v_mul_f32_e32 v42, v42, v50
	v_exp_f32_e32 v32, v32
	v_exp_f32_e32 v42, v42
	v_mul_f32_e32 v43, v43, v50
	v_mov_b32_e32 v48, v34
	v_mul_f32_e32 v34, v34, v50
	v_exp_f32_e32 v43, v43
	v_exp_f32_e32 v34, v34
	v_add_f32_e32 v40, 1.0, v40
	v_rcp_f32_e32 v40, v40
	v_add_f32_e32 v41, 1.0, v41
	v_add_f32_e32 v32, 1.0, v32
	v_rcp_f32_e32 v41, v41
	v_add_f32_e32 v42, 1.0, v42
	v_rcp_f32_e32 v52, v32
	v_mov_b32_e32 v32, v38
	v_mov_b32_e32 v33, v49
	v_rcp_f32_e32 v42, v42
	v_add_f32_e32 v43, 1.0, v43
	v_pk_mul_f32 v[32:33], v[48:49], v[32:33]
	v_add_f32_e32 v34, 1.0, v34
	v_rcp_f32_e32 v43, v43
	v_mul_f32_e32 v38, v44, v33
	v_rcp_f32_e32 v34, v34
	v_mul_f32_e32 v38, v38, v40
	v_mul_f32_e32 v40, v45, v33
	v_mul_f32_e32 v40, v40, v41
	v_mul_f32_e32 v41, v46, v33
	v_mul_f32_e32 v41, v41, v42
	v_mul_f32_e32 v42, v47, v33
	v_mul_f32_e32 v32, v32, v33
	v_mul_f32_e32 v42, v42, v43
	v_mul_f32_e32 v43, v32, v34
	v_mul_f32_e32 v32, v35, v39
	v_mul_f32_e32 v36, v36, v33
	v_mul_f32_e32 v37, v37, v33
	v_mul_f32_e32 v32, v32, v33
	v_mul_f32_e32 v33, v35, v50
	v_exp_f32_e32 v33, v33
	v_mul_f32_e32 v36, v36, v51
	v_mul_f32_e32 v37, v37, v52
	v_add_u32_e32 v39, s28, v54
	v_add_f32_e32 v33, 1.0, v33
	v_rcp_f32_e32 v33, v33
	v_cvt_pk_bf16_f32 v34, v36, v37
	v_mad_i64_i32 v[36:37], s[30:31], v39, s33, v[116:117]
	v_lshl_add_u64 v[36:37], v[36:37], 0, s[54:55]
	v_lshl_add_u64 v[36:37], v[36:37], 0, v[194:195]
	v_mul_f32_e32 v35, v32, v33
	v_cvt_pk_bf16_f32 v32, v38, v40
	v_lshl_add_u64 v[36:37], v[36:37], 0, v[118:119]
	v_add_u32_e32 v38, 0xa0, v136
	v_cvt_pk_bf16_f32 v33, v41, v42
	v_cvt_pk_bf16_f32 v35, v43, v35
	global_store_dwordx4 v[36:37], v[32:35], off
	s_nop 1
	v_lshl_add_u32 v32, v38, 4, s8
	ds_read_b128 v[32:35], v32
	s_waitcnt lgkmcnt(0)
; #define LAS __attribute__((address_space(3)))
; DEV u32x4 pack8(const float (&v)[8]) { u32x4 w; w.x = cvt_pk_bf16(v[0], v[1]); w.y = cvt_pk_bf16(v[2], v[3]); w.z = cvt_pk_bf16(v[4], v[5]); w.w = cvt_pk_bf16(v[6], v[7]); return w; }
; #define BAR __builtin_amdgcn_s_barrier()
; DEV void TileMap::operator()(int t, int& brow, int& bcol) const { int pm, pn; tile_map(t, nM, nN, pm, pn); brow = pm * 256; bcol = pn * 256; }
; DEV void TileMapRev::operator()(int t, int& brow, int& bcol) const { int pm, pn; tile_map(t, nM, nN, pm, pn); brow = (nM - 1 - pm) * 256; bcol = pn * 256; }
; template <int BMODE, class Epi, class TileFn>
; DEV void gemm_loop(LAS unsigned char* lds, const bf16_t* __restrict__ A, int lda, const bf16_t* __restrict__ B, int ldb, int K, const Epi& epi, int t0, int tstep, int tend, const TileFn& tf) {
;     ...
;         if (wr == 0) BAR;
;         epi(acc, brow, bcol, lds, par);
;         if (!has_next) break;
; #pragma unroll
;         for (int a = 0; a < 2; ++a)
; #pragma unroll
;             for (int b = 0; b < 2; ++b)
; #pragma unroll
;                 for (int m = 0; m < 4; ++m)
; #pragma unroll
;                     for (int n = 0; n < 2; ++n) acc[a][b][m][n] = (f32x4){0.f, 0.f, 0.f, 0.f};
;         brow = nrow; bcol = ncol; cA = nA; cB = nB;
;         if (wr == 1) BAR;
;     }
;     DEV void operator()(f32x4 (&acc)[2][2][4][2], int brow, int bcol, LAS unsigned char* lds, int par) const {
;         EPI_IDS
; #pragma unroll
;         for (int ai = 0; ai < 2; ++ai)
; #pragma unroll
;             for (int m = 0; m < 4; ++m) {
;                 const int lr = ai * 128 + wr * 64 + m * 16 + fr, row = brow + lr;
;                 const f32x4 s4 = *(const LAS f32x4*)(lds + LDS_EX + par * 4096 + lr * 16);
;                 const float rs = rsqrtf(((s4[0] + s4[1]) + (s4[2] + s4[3])) * (1.0f / 1024.0f) + EPS);
;                 float o[8];
;                 const float rs2 = rs * rs, ce = rs * -1.4426950408889634f;
; #pragma unroll
;                 for (int bj = 0; bj < 2; ++bj) {
;                     const f32x4 g = acc[ai][bj][m][0], u = acc[ai][bj][m][1];
; #pragma unroll
;                     for (int j = 0; j < 4; ++j) o[bj * 4 + j] = (g[j] * u[j]) * rs2 * __builtin_amdgcn_rcpf(1.0f + __builtin_amdgcn_exp2f(g[j] * ce));
;                 }
;                 *(u32x4*)(act + (size_t)row * DFF + (bcol >> 1) + wc * 32 + fq * 8) = pack8(o);
;             }
	v_mov_b32_e32 v36, v33
	v_mov_b32_e32 v37, v34
	v_mov_b32_e32 v33, v35
	v_pk_add_f32 v[32:33], v[36:37], v[32:33]
	v_mul_f32_e32 v35, v20, v16
	v_add_f32_e32 v32, v32, v33
	v_fmamk_f32 v32, v32, 0x3a800000, v189
	v_cmp_gt_f32_e32 vcc, s24, v32
	v_mul_f32_e32 v33, 0x4b800000, v32
	v_mul_f32_e32 v36, v21, v17
	v_cndmask_b32_e32 v32, v32, v33, vcc
	v_rsq_f32_e32 v32, v32
	s_nop 0
	v_mul_f32_e32 v33, 0x45800000, v32
	v_cndmask_b32_e32 v33, v32, v33, vcc
	v_mul_f32_e32 v34, 0xbfb8aa3b, v33
	v_mul_f32_e32 v16, v20, v34
	v_exp_f32_e32 v16, v16
	v_mov_b32_e32 v32, v22
	v_mul_f32_e32 v22, v22, v34
	v_exp_f32_e32 v22, v22
	v_add_f32_e32 v16, 1.0, v16
	v_rcp_f32_e32 v20, v16
	v_mul_f32_e32 v16, v21, v34
	v_exp_f32_e32 v16, v16
	v_add_f32_e32 v22, 1.0, v22
	v_rcp_f32_e32 v22, v22
	v_mov_b32_e32 v17, v33
	v_add_f32_e32 v16, 1.0, v16
	v_rcp_f32_e32 v21, v16
	v_mov_b32_e32 v16, v18
	v_pk_mul_f32 v[16:17], v[32:33], v[16:17]
	v_mul_f32_e32 v28, v28, v34
	v_mul_f32_e32 v16, v16, v17
	v_mul_f32_e32 v18, v24, v17
	v_mul_f32_e32 v24, v25, v17
	v_mul_f32_e32 v25, v26, v17
	v_mul_f32_e32 v26, v27, v17
	v_mul_f32_e32 v27, v35, v17
	v_mul_f32_e32 v22, v16, v22
	v_mul_f32_e32 v16, v23, v19
	v_exp_f32_e32 v28, v28
	v_mul_f32_e32 v29, v29, v34
	v_mul_f32_e32 v20, v27, v20
	v_mul_f32_e32 v27, v36, v17
	v_mul_f32_e32 v16, v16, v17
	v_mul_f32_e32 v17, v23, v34
	v_exp_f32_e32 v29, v29
	v_exp_f32_e32 v17, v17
	v_add_f32_e32 v28, 1.0, v28
	v_mul_f32_e32 v30, v30, v34
	v_mul_f32_e32 v31, v31, v34
	v_rcp_f32_e32 v28, v28
	v_add_f32_e32 v29, 1.0, v29
	v_exp_f32_e32 v30, v30
	v_exp_f32_e32 v31, v31
	v_add_f32_e32 v17, 1.0, v17
	v_rcp_f32_e32 v29, v29
	v_rcp_f32_e32 v17, v17
	v_add_f32_e32 v30, 1.0, v30
	v_add_f32_e32 v31, 1.0, v31
	v_mul_f32_e32 v18, v18, v28
	v_mul_f32_e32 v21, v27, v21
	v_add_u32_e32 v23, s28, v38
	v_rcp_f32_e32 v30, v30
	v_rcp_f32_e32 v31, v31
	v_mul_f32_e32 v24, v24, v29
	v_mul_f32_e32 v19, v16, v17
	v_cvt_pk_bf16_f32 v16, v18, v24
	v_cvt_pk_bf16_f32 v18, v20, v21
	v_mad_i64_i32 v[20:21], s[30:31], v23, s33, v[116:117]
	v_lshl_add_u64 v[20:21], v[20:21], 0, s[54:55]
	v_lshl_add_u64 v[20:21], v[20:21], 0, v[194:195]
	v_cvt_pk_bf16_f32 v19, v22, v19
	v_lshl_add_u64 v[20:21], v[20:21], 0, v[118:119]
	v_add_u32_e32 v22, 0xb0, v136
	v_mul_f32_e32 v25, v25, v30
	v_mul_f32_e32 v26, v26, v31
	v_cvt_pk_bf16_f32 v17, v25, v26
	global_store_dwordx4 v[20:21], v[16:19], off
	s_nop 1
	v_lshl_add_u32 v16, v22, 4, s8
	ds_read_b128 v[16:19], v16
	s_waitcnt lgkmcnt(0)
	v_mov_b32_e32 v20, v17
	v_mov_b32_e32 v21, v18
	v_mov_b32_e32 v17, v19
	v_pk_add_f32 v[16:17], v[20:21], v[16:17]
	s_nop 0
	v_add_f32_e32 v16, v16, v17
	v_fmamk_f32 v16, v16, 0x3a800000, v189
	v_cmp_gt_f32_e32 vcc, s24, v16
	v_mul_f32_e32 v17, 0x4b800000, v16
	s_nop 0
	v_cndmask_b32_e32 v16, v16, v17, vcc
	v_rsq_f32_e32 v16, v16
	s_nop 0
	v_mul_f32_e32 v17, 0x45800000, v16
	v_cndmask_b32_e32 v17, v16, v17, vcc
	v_mul_f32_e32 v18, 0xbfb8aa3b, v17
	v_mul_f32_e32 v0, v0, v18
	v_exp_f32_e32 v0, v0
	v_mul_f32_e32 v8, v8, v18
	v_exp_f32_e32 v8, v8
	v_mul_f32_e32 v9, v9, v18
	v_add_f32_e32 v0, 1.0, v0
	v_rcp_f32_e32 v19, v0
	v_mul_f32_e32 v0, v1, v18
	v_exp_f32_e32 v9, v9
	v_mul_f32_e32 v10, v10, v18
	v_exp_f32_e32 v0, v0
	v_exp_f32_e32 v10, v10
	v_mul_f32_e32 v11, v11, v18
	v_mov_b32_e32 v16, v2
	v_mul_f32_e32 v2, v2, v18
	v_exp_f32_e32 v11, v11
	v_exp_f32_e32 v2, v2
	v_add_f32_e32 v8, 1.0, v8
	v_rcp_f32_e32 v8, v8
	v_add_f32_e32 v9, 1.0, v9
	v_add_f32_e32 v0, 1.0, v0
	v_rcp_f32_e32 v9, v9
	v_add_f32_e32 v10, 1.0, v10
	v_rcp_f32_e32 v20, v0
	v_mov_b32_e32 v0, v6
	v_mov_b32_e32 v1, v17
	v_rcp_f32_e32 v10, v10
	v_add_f32_e32 v11, 1.0, v11
	v_pk_mul_f32 v[0:1], v[16:17], v[0:1]
	v_add_f32_e32 v2, 1.0, v2
	v_rcp_f32_e32 v11, v11
	v_mul_f32_e32 v6, v12, v1
	v_rcp_f32_e32 v2, v2
	v_mul_f32_e32 v6, v6, v8
	v_mul_f32_e32 v8, v13, v1
	v_mul_f32_e32 v8, v8, v9
	v_mul_f32_e32 v9, v14, v1
	v_mul_f32_e32 v9, v9, v10
	v_mul_f32_e32 v10, v15, v1
	v_mul_f32_e32 v0, v0, v1
	v_mul_f32_e32 v10, v10, v11
	v_mul_f32_e32 v11, v0, v2
	v_mul_f32_e32 v0, v3, v7
	v_mul_f32_e32 v4, v4, v1
	v_mul_f32_e32 v5, v5, v1
	v_mul_f32_e32 v0, v0, v1
	v_mul_f32_e32 v1, v3, v18
	v_exp_f32_e32 v1, v1
	v_mul_f32_e32 v4, v4, v19
	v_mul_f32_e32 v5, v5, v20
	v_add_u32_e32 v7, s28, v22
	v_add_f32_e32 v1, 1.0, v1
	v_rcp_f32_e32 v1, v1
	v_cvt_pk_bf16_f32 v2, v4, v5
	v_mad_i64_i32 v[4:5], s[8:9], v7, s33, v[116:117]
	v_lshl_add_u64 v[4:5], v[4:5], 0, s[54:55]
	v_lshl_add_u64 v[4:5], v[4:5], 0, v[194:195]
	v_mul_f32_e32 v3, v0, v1
	v_lshl_add_u64 v[4:5], v[4:5], 0, v[118:119]
	s_mov_b64 s[8:9], -1
	s_andn2_b64 vcc, exec, s[76:77]
	v_cvt_pk_bf16_f32 v0, v6, v8
	v_cvt_pk_bf16_f32 v1, v9, v10
	v_cvt_pk_bf16_f32 v3, v11, v3
	global_store_dwordx4 v[4:5], v[0:3], off
	s_cbranch_vccnz .LBB0_1332
	s_and_saveexec_b64 s[8:9], s[38:39]
	s_cbranch_execz .LBB0_1331
	s_barrier
	s_branch .LBB0_1331
